# v17: v16 + nt on the final-layer f32 output stores (never re-read)
# baseline (speedup 1.0000x reference)
; __device__ __forceinline__ unsigned cvtpk(float lo, float hi) { f32x2 v = {lo, hi}; bf16x2_t b = __builtin_convertvector(v, bf16x2_t); return __builtin_bit_cast(unsigned, b); }
;     __device__ __forceinline__ void operator()(const f32x4 (&acc)[2][2][4][2], const Unit& u, int wr, int wc, int fr, int fq) const {
;     ...
;                 for (int bj = 0; bj < 2; ++bj) { const int col = u.pn * BM + bj * HALF + wc * 32 + 8 * fq;
;                     f32x4 v0, v1;
;                     if (xin_p) { const float* xr = (row < MP ? xin_p + (size_t)row * DM : xin_s + (size_t)(row - MP) * DM) + col; v0 = *(const f32x4*)xr; v1 = *(const f32x4*)(xr + 4); }
;                     else { const u32x4 w = *(const u32x4*)(XR + (size_t)row * DM + col);
;                         v0 = (f32x4){__uint_as_float(w.x << 16), __uint_as_float(w.x & 0xffff0000u), __uint_as_float(w.y << 16), __uint_as_float(w.y & 0xffff0000u)};
;                         v1 = (f32x4){__uint_as_float(w.z << 16), __uint_as_float(w.z & 0xffff0000u), __uint_as_float(w.w << 16), __uint_as_float(w.w & 0xffff0000u)}; }
;                     v0 = v0 + acc[ai][bj][m][0]; v1 = v1 + acc[ai][bj][m][1];
;                     if (fout) { *(f32x4*)(fout + (size_t)row * DM + col) = v0; *(f32x4*)(fout + (size_t)row * DM + col + 4) = v1; }
;                     else { u32x4 w; w.x = cvtpk(v0[0], v0[1]); w.y = cvtpk(v0[2], v0[3]); w.z = cvtpk(v1[0], v1[1]); w.w = cvtpk(v1[2], v1[3]); *(u32x4*)(XR + (size_t)row * DM + col) = w; }
.LBB0_882:
	v_lshl_add_u32 v140, s45, 8, v154
	v_ashrrev_i32_e32 v141, 31, v140
	v_lshl_or_b32 v138, s44, 8, v156
	v_lshlrev_b64 v[142:143], 11, v[140:141]
	v_lshl_add_u64 v[142:143], s[12:13], 0, v[142:143]
	v_ashrrev_i32_e32 v139, 31, v138
	v_lshl_add_u64 v[142:143], v[138:139], 1, v[142:143]
	global_load_dwordx4 v[158:161], v[142:143], off
	v_cndmask_b32_e64 v152, 0, 1, s[20:21]
	v_cmp_ne_u32_e64 s[6:7], 1, v152
	v_lshlrev_b64 v[152:153], 10, v[140:141]
	s_andn2_b64 vcc, exec, s[20:21]
	v_lshl_add_u64 v[152:153], v[152:153], 2, s[16:17]
	s_waitcnt vmcnt(0)
	v_lshlrev_b32_e32 v162, 16, v158
	v_and_b32_e32 v163, 0xffff0000, v158
	v_lshlrev_b32_e32 v158, 16, v159
	v_and_b32_e32 v159, 0xffff0000, v159
	v_lshlrev_b32_e32 v164, 16, v160
	v_and_b32_e32 v165, 0xffff0000, v160
	v_lshlrev_b32_e32 v160, 16, v161
	v_and_b32_e32 v161, 0xffff0000, v161
	v_pk_add_f32 v[126:127], v[126:127], v[158:159]
	v_pk_add_f32 v[124:125], v[124:125], v[162:163]
	v_pk_add_f32 v[122:123], v[122:123], v[160:161]
	v_pk_add_f32 v[120:121], v[120:121], v[164:165]
	s_cbranch_vccnz .LBB0_965
	v_lshl_add_u64 v[158:159], v[138:139], 2, v[152:153]
	global_store_dwordx4 v[158:159], v[124:127], off nt
	global_store_dwordx4 v[158:159], v[120:123], off offset:16 nt
	s_cbranch_execnz .LBB0_885

; __device__ __forceinline__ unsigned cvtpk(float lo, float hi) { f32x2 v = {lo, hi}; bf16x2_t b = __builtin_convertvector(v, bf16x2_t); return __builtin_bit_cast(unsigned, b); }
;     __device__ __forceinline__ void operator()(const f32x4 (&acc)[2][2][4][2], const Unit& u, int wr, int wc, int fr, int fq) const {
;     ...
;                 for (int bj = 0; bj < 2; ++bj) { const int col = u.pn * BM + bj * HALF + wc * 32 + 8 * fq;
;                     f32x4 v0, v1;
;                     if (xin_p) { const float* xr = (row < MP ? xin_p + (size_t)row * DM : xin_s + (size_t)(row - MP) * DM) + col; v0 = *(const f32x4*)xr; v1 = *(const f32x4*)(xr + 4); }
;                     else { const u32x4 w = *(const u32x4*)(XR + (size_t)row * DM + col);
;                         v0 = (f32x4){__uint_as_float(w.x << 16), __uint_as_float(w.x & 0xffff0000u), __uint_as_float(w.y << 16), __uint_as_float(w.y & 0xffff0000u)};
;                         v1 = (f32x4){__uint_as_float(w.z << 16), __uint_as_float(w.z & 0xffff0000u), __uint_as_float(w.w << 16), __uint_as_float(w.w & 0xffff0000u)}; }
;                     v0 = v0 + acc[ai][bj][m][0]; v1 = v1 + acc[ai][bj][m][1];
;                     if (fout) { *(f32x4*)(fout + (size_t)row * DM + col) = v0; *(f32x4*)(fout + (size_t)row * DM + col + 4) = v1; }
;                     else { u32x4 w; w.x = cvtpk(v0[0], v0[1]); w.y = cvtpk(v0[2], v0[3]); w.z = cvtpk(v1[0], v1[1]); w.w = cvtpk(v1[2], v1[3]); *(u32x4*)(XR + (size_t)row * DM + col) = w; }
.LBB0_885:
	global_load_dwordx4 v[158:161], v[142:143], off offset:256
	s_and_b64 vcc, exec, s[6:7]
	s_waitcnt vmcnt(0)
	v_lshlrev_b32_e32 v162, 16, v158
	v_and_b32_e32 v163, 0xffff0000, v158
	v_lshlrev_b32_e32 v158, 16, v159
	v_and_b32_e32 v159, 0xffff0000, v159
	v_lshlrev_b32_e32 v164, 16, v160
	v_and_b32_e32 v165, 0xffff0000, v160
	v_lshlrev_b32_e32 v160, 16, v161
	v_and_b32_e32 v161, 0xffff0000, v161
	v_pk_add_f32 v[118:119], v[118:119], v[158:159]
	v_pk_add_f32 v[116:117], v[116:117], v[162:163]
	v_pk_add_f32 v[114:115], v[114:115], v[160:161]
	v_pk_add_f32 v[112:113], v[112:113], v[164:165]
	s_cbranch_vccnz .LBB0_966
	v_lshl_add_u64 v[152:153], v[138:139], 2, v[152:153]
	global_store_dwordx4 v[152:153], v[116:119], off offset:512 nt
	global_store_dwordx4 v[152:153], v[112:115], off offset:528 nt
	s_cbranch_execnz .LBB0_888

; __device__ __forceinline__ unsigned cvtpk(float lo, float hi) { f32x2 v = {lo, hi}; bf16x2_t b = __builtin_convertvector(v, bf16x2_t); return __builtin_bit_cast(unsigned, b); }
;     __device__ __forceinline__ void operator()(const f32x4 (&acc)[2][2][4][2], const Unit& u, int wr, int wc, int fr, int fq) const {
;     ...
;                 for (int bj = 0; bj < 2; ++bj) { const int col = u.pn * BM + bj * HALF + wc * 32 + 8 * fq;
;                     f32x4 v0, v1;
;                     if (xin_p) { const float* xr = (row < MP ? xin_p + (size_t)row * DM : xin_s + (size_t)(row - MP) * DM) + col; v0 = *(const f32x4*)xr; v1 = *(const f32x4*)(xr + 4); }
;                     else { const u32x4 w = *(const u32x4*)(XR + (size_t)row * DM + col);
;                         v0 = (f32x4){__uint_as_float(w.x << 16), __uint_as_float(w.x & 0xffff0000u), __uint_as_float(w.y << 16), __uint_as_float(w.y & 0xffff0000u)};
;                         v1 = (f32x4){__uint_as_float(w.z << 16), __uint_as_float(w.z & 0xffff0000u), __uint_as_float(w.w << 16), __uint_as_float(w.w & 0xffff0000u)}; }
;                     v0 = v0 + acc[ai][bj][m][0]; v1 = v1 + acc[ai][bj][m][1];
;                     if (fout) { *(f32x4*)(fout + (size_t)row * DM + col) = v0; *(f32x4*)(fout + (size_t)row * DM + col + 4) = v1; }
;                     else { u32x4 w; w.x = cvtpk(v0[0], v0[1]); w.y = cvtpk(v0[2], v0[3]); w.z = cvtpk(v1[0], v1[1]); w.w = cvtpk(v1[2], v1[3]); *(u32x4*)(XR + (size_t)row * DM + col) = w; }
.LBB0_892:
	v_or_b32_e32 v112, 16, v140
	v_ashrrev_i32_e32 v113, 31, v112
	v_lshlrev_b64 v[114:115], 11, v[112:113]
	v_lshl_add_u64 v[114:115], s[12:13], 0, v[114:115]
	v_lshl_add_u64 v[114:115], v[138:139], 1, v[114:115]
	global_load_dwordx4 v[116:119], v[114:115], off
	v_lshlrev_b64 v[120:121], 10, v[112:113]
	s_and_b64 vcc, exec, s[6:7]
	s_waitcnt vmcnt(0)
	v_lshlrev_b32_e32 v122, 16, v116
	v_and_b32_e32 v123, 0xffff0000, v116
	v_lshlrev_b32_e32 v116, 16, v117
	v_and_b32_e32 v117, 0xffff0000, v117
	v_lshlrev_b32_e32 v124, 16, v118
	v_and_b32_e32 v125, 0xffff0000, v118
	v_lshlrev_b32_e32 v118, 16, v119
	v_and_b32_e32 v119, 0xffff0000, v119
	v_pk_add_f32 v[110:111], v[110:111], v[116:117]
	v_pk_add_f32 v[108:109], v[108:109], v[122:123]
	v_pk_add_f32 v[106:107], v[106:107], v[118:119]
	v_pk_add_f32 v[104:105], v[104:105], v[124:125]
	v_lshl_add_u64 v[116:117], v[120:121], 2, s[16:17]
	s_cbranch_vccnz .LBB0_967
	v_lshl_add_u64 v[118:119], v[138:139], 2, v[116:117]
	global_store_dwordx4 v[118:119], v[108:111], off nt
	global_store_dwordx4 v[118:119], v[104:107], off offset:16 nt
	s_cbranch_execnz .LBB0_895

; __device__ __forceinline__ unsigned cvtpk(float lo, float hi) { f32x2 v = {lo, hi}; bf16x2_t b = __builtin_convertvector(v, bf16x2_t); return __builtin_bit_cast(unsigned, b); }
;     __device__ __forceinline__ void operator()(const f32x4 (&acc)[2][2][4][2], const Unit& u, int wr, int wc, int fr, int fq) const {
;     ...
;                 for (int bj = 0; bj < 2; ++bj) { const int col = u.pn * BM + bj * HALF + wc * 32 + 8 * fq;
;                     f32x4 v0, v1;
;                     if (xin_p) { const float* xr = (row < MP ? xin_p + (size_t)row * DM : xin_s + (size_t)(row - MP) * DM) + col; v0 = *(const f32x4*)xr; v1 = *(const f32x4*)(xr + 4); }
;                     else { const u32x4 w = *(const u32x4*)(XR + (size_t)row * DM + col);
;                         v0 = (f32x4){__uint_as_float(w.x << 16), __uint_as_float(w.x & 0xffff0000u), __uint_as_float(w.y << 16), __uint_as_float(w.y & 0xffff0000u)};
;                         v1 = (f32x4){__uint_as_float(w.z << 16), __uint_as_float(w.z & 0xffff0000u), __uint_as_float(w.w << 16), __uint_as_float(w.w & 0xffff0000u)}; }
;                     v0 = v0 + acc[ai][bj][m][0]; v1 = v1 + acc[ai][bj][m][1];
;                     if (fout) { *(f32x4*)(fout + (size_t)row * DM + col) = v0; *(f32x4*)(fout + (size_t)row * DM + col + 4) = v1; }
;                     else { u32x4 w; w.x = cvtpk(v0[0], v0[1]); w.y = cvtpk(v0[2], v0[3]); w.z = cvtpk(v1[0], v1[1]); w.w = cvtpk(v1[2], v1[3]); *(u32x4*)(XR + (size_t)row * DM + col) = w; }
.LBB0_895:
	global_load_dwordx4 v[118:121], v[114:115], off offset:256
	s_and_b64 vcc, exec, s[6:7]
	s_waitcnt vmcnt(0)
	v_lshlrev_b32_e32 v122, 16, v118
	v_and_b32_e32 v123, 0xffff0000, v118
	v_lshlrev_b32_e32 v118, 16, v119
	v_and_b32_e32 v119, 0xffff0000, v119
	v_lshlrev_b32_e32 v124, 16, v120
	v_and_b32_e32 v125, 0xffff0000, v120
	v_lshlrev_b32_e32 v120, 16, v121
	v_and_b32_e32 v121, 0xffff0000, v121
	v_pk_add_f32 v[102:103], v[102:103], v[118:119]
	v_pk_add_f32 v[100:101], v[100:101], v[122:123]
	v_pk_add_f32 v[98:99], v[98:99], v[120:121]
	v_pk_add_f32 v[96:97], v[96:97], v[124:125]
	s_cbranch_vccnz .LBB0_968
	v_lshl_add_u64 v[116:117], v[138:139], 2, v[116:117]
	global_store_dwordx4 v[116:117], v[100:103], off offset:512 nt
	global_store_dwordx4 v[116:117], v[96:99], off offset:528 nt
	s_cbranch_execnz .LBB0_898

; __device__ __forceinline__ unsigned cvtpk(float lo, float hi) { f32x2 v = {lo, hi}; bf16x2_t b = __builtin_convertvector(v, bf16x2_t); return __builtin_bit_cast(unsigned, b); }
;     __device__ __forceinline__ void operator()(const f32x4 (&acc)[2][2][4][2], const Unit& u, int wr, int wc, int fr, int fq) const {
;     ...
;                 for (int bj = 0; bj < 2; ++bj) { const int col = u.pn * BM + bj * HALF + wc * 32 + 8 * fq;
;                     f32x4 v0, v1;
;                     if (xin_p) { const float* xr = (row < MP ? xin_p + (size_t)row * DM : xin_s + (size_t)(row - MP) * DM) + col; v0 = *(const f32x4*)xr; v1 = *(const f32x4*)(xr + 4); }
;                     else { const u32x4 w = *(const u32x4*)(XR + (size_t)row * DM + col);
;                         v0 = (f32x4){__uint_as_float(w.x << 16), __uint_as_float(w.x & 0xffff0000u), __uint_as_float(w.y << 16), __uint_as_float(w.y & 0xffff0000u)};
;                         v1 = (f32x4){__uint_as_float(w.z << 16), __uint_as_float(w.z & 0xffff0000u), __uint_as_float(w.w << 16), __uint_as_float(w.w & 0xffff0000u)}; }
;                     v0 = v0 + acc[ai][bj][m][0]; v1 = v1 + acc[ai][bj][m][1];
;                     if (fout) { *(f32x4*)(fout + (size_t)row * DM + col) = v0; *(f32x4*)(fout + (size_t)row * DM + col + 4) = v1; }
;                     else { u32x4 w; w.x = cvtpk(v0[0], v0[1]); w.y = cvtpk(v0[2], v0[3]); w.z = cvtpk(v1[0], v1[1]); w.w = cvtpk(v1[2], v1[3]); *(u32x4*)(XR + (size_t)row * DM + col) = w; }
.LBB0_902:
	v_or_b32_e32 v96, 32, v140
	v_ashrrev_i32_e32 v97, 31, v96
	v_lshlrev_b64 v[98:99], 11, v[96:97]
	v_lshl_add_u64 v[98:99], s[12:13], 0, v[98:99]
	v_lshl_add_u64 v[98:99], v[138:139], 1, v[98:99]
	global_load_dwordx4 v[100:103], v[98:99], off
	v_lshlrev_b64 v[104:105], 10, v[96:97]
	s_and_b64 vcc, exec, s[6:7]
	s_waitcnt vmcnt(0)
	v_lshlrev_b32_e32 v106, 16, v100
	v_and_b32_e32 v107, 0xffff0000, v100
	v_lshlrev_b32_e32 v100, 16, v101
	v_and_b32_e32 v101, 0xffff0000, v101
	v_lshlrev_b32_e32 v108, 16, v102
	v_and_b32_e32 v109, 0xffff0000, v102
	v_lshlrev_b32_e32 v102, 16, v103
	v_and_b32_e32 v103, 0xffff0000, v103
	v_pk_add_f32 v[94:95], v[94:95], v[100:101]
	v_pk_add_f32 v[92:93], v[92:93], v[106:107]
	v_pk_add_f32 v[90:91], v[90:91], v[102:103]
	v_pk_add_f32 v[88:89], v[88:89], v[108:109]
	v_lshl_add_u64 v[100:101], v[104:105], 2, s[16:17]
	s_cbranch_vccnz .LBB0_969
	v_lshl_add_u64 v[102:103], v[138:139], 2, v[100:101]
	global_store_dwordx4 v[102:103], v[92:95], off nt
	global_store_dwordx4 v[102:103], v[88:91], off offset:16 nt
	s_cbranch_execnz .LBB0_905

; __device__ __forceinline__ unsigned cvtpk(float lo, float hi) { f32x2 v = {lo, hi}; bf16x2_t b = __builtin_convertvector(v, bf16x2_t); return __builtin_bit_cast(unsigned, b); }
;     __device__ __forceinline__ void operator()(const f32x4 (&acc)[2][2][4][2], const Unit& u, int wr, int wc, int fr, int fq) const {
;     ...
;                 for (int bj = 0; bj < 2; ++bj) { const int col = u.pn * BM + bj * HALF + wc * 32 + 8 * fq;
;                     f32x4 v0, v1;
;                     if (xin_p) { const float* xr = (row < MP ? xin_p + (size_t)row * DM : xin_s + (size_t)(row - MP) * DM) + col; v0 = *(const f32x4*)xr; v1 = *(const f32x4*)(xr + 4); }
;                     else { const u32x4 w = *(const u32x4*)(XR + (size_t)row * DM + col);
;                         v0 = (f32x4){__uint_as_float(w.x << 16), __uint_as_float(w.x & 0xffff0000u), __uint_as_float(w.y << 16), __uint_as_float(w.y & 0xffff0000u)};
;                         v1 = (f32x4){__uint_as_float(w.z << 16), __uint_as_float(w.z & 0xffff0000u), __uint_as_float(w.w << 16), __uint_as_float(w.w & 0xffff0000u)}; }
;                     v0 = v0 + acc[ai][bj][m][0]; v1 = v1 + acc[ai][bj][m][1];
;                     if (fout) { *(f32x4*)(fout + (size_t)row * DM + col) = v0; *(f32x4*)(fout + (size_t)row * DM + col + 4) = v1; }
;                     else { u32x4 w; w.x = cvtpk(v0[0], v0[1]); w.y = cvtpk(v0[2], v0[3]); w.z = cvtpk(v1[0], v1[1]); w.w = cvtpk(v1[2], v1[3]); *(u32x4*)(XR + (size_t)row * DM + col) = w; }
.LBB0_905:
	global_load_dwordx4 v[102:105], v[98:99], off offset:256
	s_and_b64 vcc, exec, s[6:7]
	s_waitcnt vmcnt(0)
	v_lshlrev_b32_e32 v106, 16, v102
	v_and_b32_e32 v107, 0xffff0000, v102
	v_lshlrev_b32_e32 v102, 16, v103
	v_and_b32_e32 v103, 0xffff0000, v103
	v_lshlrev_b32_e32 v108, 16, v104
	v_and_b32_e32 v109, 0xffff0000, v104
	v_lshlrev_b32_e32 v104, 16, v105
	v_and_b32_e32 v105, 0xffff0000, v105
	v_pk_add_f32 v[86:87], v[86:87], v[102:103]
	v_pk_add_f32 v[84:85], v[84:85], v[106:107]
	v_pk_add_f32 v[82:83], v[82:83], v[104:105]
	v_pk_add_f32 v[80:81], v[80:81], v[108:109]
	s_cbranch_vccnz .LBB0_970
	v_lshl_add_u64 v[100:101], v[138:139], 2, v[100:101]
	global_store_dwordx4 v[100:101], v[84:87], off offset:512 nt
	global_store_dwordx4 v[100:101], v[80:83], off offset:528 nt
	s_cbranch_execnz .LBB0_908

; __device__ __forceinline__ unsigned cvtpk(float lo, float hi) { f32x2 v = {lo, hi}; bf16x2_t b = __builtin_convertvector(v, bf16x2_t); return __builtin_bit_cast(unsigned, b); }
;     __device__ __forceinline__ void operator()(const f32x4 (&acc)[2][2][4][2], const Unit& u, int wr, int wc, int fr, int fq) const {
;     ...
;                 for (int bj = 0; bj < 2; ++bj) { const int col = u.pn * BM + bj * HALF + wc * 32 + 8 * fq;
;                     f32x4 v0, v1;
;                     if (xin_p) { const float* xr = (row < MP ? xin_p + (size_t)row * DM : xin_s + (size_t)(row - MP) * DM) + col; v0 = *(const f32x4*)xr; v1 = *(const f32x4*)(xr + 4); }
;                     else { const u32x4 w = *(const u32x4*)(XR + (size_t)row * DM + col);
;                         v0 = (f32x4){__uint_as_float(w.x << 16), __uint_as_float(w.x & 0xffff0000u), __uint_as_float(w.y << 16), __uint_as_float(w.y & 0xffff0000u)};
;                         v1 = (f32x4){__uint_as_float(w.z << 16), __uint_as_float(w.z & 0xffff0000u), __uint_as_float(w.w << 16), __uint_as_float(w.w & 0xffff0000u)}; }
;                     v0 = v0 + acc[ai][bj][m][0]; v1 = v1 + acc[ai][bj][m][1];
;                     if (fout) { *(f32x4*)(fout + (size_t)row * DM + col) = v0; *(f32x4*)(fout + (size_t)row * DM + col + 4) = v1; }
;                     else { u32x4 w; w.x = cvtpk(v0[0], v0[1]); w.y = cvtpk(v0[2], v0[3]); w.z = cvtpk(v1[0], v1[1]); w.w = cvtpk(v1[2], v1[3]); *(u32x4*)(XR + (size_t)row * DM + col) = w; }
.LBB0_912:
	v_or_b32_e32 v80, 48, v140
	v_ashrrev_i32_e32 v81, 31, v80
	v_lshlrev_b64 v[82:83], 11, v[80:81]
	v_lshl_add_u64 v[82:83], s[12:13], 0, v[82:83]
	v_lshl_add_u64 v[82:83], v[138:139], 1, v[82:83]
	global_load_dwordx4 v[84:87], v[82:83], off
	v_lshlrev_b64 v[88:89], 10, v[80:81]
	s_and_b64 vcc, exec, s[6:7]
	s_waitcnt vmcnt(0)
	v_lshlrev_b32_e32 v90, 16, v84
	v_and_b32_e32 v91, 0xffff0000, v84
	v_lshlrev_b32_e32 v84, 16, v85
	v_and_b32_e32 v85, 0xffff0000, v85
	v_lshlrev_b32_e32 v92, 16, v86
	v_and_b32_e32 v93, 0xffff0000, v86
	v_lshlrev_b32_e32 v86, 16, v87
	v_and_b32_e32 v87, 0xffff0000, v87
	v_pk_add_f32 v[78:79], v[78:79], v[84:85]
	v_pk_add_f32 v[76:77], v[76:77], v[90:91]
	v_pk_add_f32 v[74:75], v[74:75], v[86:87]
	v_pk_add_f32 v[72:73], v[72:73], v[92:93]
	v_lshl_add_u64 v[84:85], v[88:89], 2, s[16:17]
	s_cbranch_vccnz .LBB0_971
	v_lshl_add_u64 v[86:87], v[138:139], 2, v[84:85]
	global_store_dwordx4 v[86:87], v[76:79], off nt
	global_store_dwordx4 v[86:87], v[72:75], off offset:16 nt
	s_cbranch_execnz .LBB0_915

; __device__ __forceinline__ unsigned cvtpk(float lo, float hi) { f32x2 v = {lo, hi}; bf16x2_t b = __builtin_convertvector(v, bf16x2_t); return __builtin_bit_cast(unsigned, b); }
;     __device__ __forceinline__ void operator()(const f32x4 (&acc)[2][2][4][2], const Unit& u, int wr, int wc, int fr, int fq) const {
;     ...
;                 for (int bj = 0; bj < 2; ++bj) { const int col = u.pn * BM + bj * HALF + wc * 32 + 8 * fq;
;                     f32x4 v0, v1;
;                     if (xin_p) { const float* xr = (row < MP ? xin_p + (size_t)row * DM : xin_s + (size_t)(row - MP) * DM) + col; v0 = *(const f32x4*)xr; v1 = *(const f32x4*)(xr + 4); }
;                     else { const u32x4 w = *(const u32x4*)(XR + (size_t)row * DM + col);
;                         v0 = (f32x4){__uint_as_float(w.x << 16), __uint_as_float(w.x & 0xffff0000u), __uint_as_float(w.y << 16), __uint_as_float(w.y & 0xffff0000u)};
;                         v1 = (f32x4){__uint_as_float(w.z << 16), __uint_as_float(w.z & 0xffff0000u), __uint_as_float(w.w << 16), __uint_as_float(w.w & 0xffff0000u)}; }
;                     v0 = v0 + acc[ai][bj][m][0]; v1 = v1 + acc[ai][bj][m][1];
;                     if (fout) { *(f32x4*)(fout + (size_t)row * DM + col) = v0; *(f32x4*)(fout + (size_t)row * DM + col + 4) = v1; }
;                     else { u32x4 w; w.x = cvtpk(v0[0], v0[1]); w.y = cvtpk(v0[2], v0[3]); w.z = cvtpk(v1[0], v1[1]); w.w = cvtpk(v1[2], v1[3]); *(u32x4*)(XR + (size_t)row * DM + col) = w; }
.LBB0_915:
	global_load_dwordx4 v[86:89], v[82:83], off offset:256
	s_and_b64 vcc, exec, s[6:7]
	s_waitcnt vmcnt(0)
	v_lshlrev_b32_e32 v90, 16, v86
	v_and_b32_e32 v91, 0xffff0000, v86
	v_lshlrev_b32_e32 v86, 16, v87
	v_and_b32_e32 v87, 0xffff0000, v87
	v_lshlrev_b32_e32 v92, 16, v88
	v_and_b32_e32 v93, 0xffff0000, v88
	v_lshlrev_b32_e32 v88, 16, v89
	v_and_b32_e32 v89, 0xffff0000, v89
	v_pk_add_f32 v[70:71], v[70:71], v[86:87]
	v_pk_add_f32 v[68:69], v[68:69], v[90:91]
	v_pk_add_f32 v[66:67], v[66:67], v[88:89]
	v_pk_add_f32 v[64:65], v[64:65], v[92:93]
	s_cbranch_vccnz .LBB0_972
	v_lshl_add_u64 v[84:85], v[138:139], 2, v[84:85]
	global_store_dwordx4 v[84:85], v[68:71], off offset:512 nt
	global_store_dwordx4 v[84:85], v[64:67], off offset:528 nt
	s_cbranch_execnz .LBB0_918

; __device__ __forceinline__ unsigned cvtpk(float lo, float hi) { f32x2 v = {lo, hi}; bf16x2_t b = __builtin_convertvector(v, bf16x2_t); return __builtin_bit_cast(unsigned, b); }
;     __device__ __forceinline__ void operator()(const f32x4 (&acc)[2][2][4][2], const Unit& u, int wr, int wc, int fr, int fq) const {
;     ...
;                 for (int bj = 0; bj < 2; ++bj) { const int col = u.pn * BM + bj * HALF + wc * 32 + 8 * fq;
;                     f32x4 v0, v1;
;                     if (xin_p) { const float* xr = (row < MP ? xin_p + (size_t)row * DM : xin_s + (size_t)(row - MP) * DM) + col; v0 = *(const f32x4*)xr; v1 = *(const f32x4*)(xr + 4); }
;                     else { const u32x4 w = *(const u32x4*)(XR + (size_t)row * DM + col);
;                         v0 = (f32x4){__uint_as_float(w.x << 16), __uint_as_float(w.x & 0xffff0000u), __uint_as_float(w.y << 16), __uint_as_float(w.y & 0xffff0000u)};
;                         v1 = (f32x4){__uint_as_float(w.z << 16), __uint_as_float(w.z & 0xffff0000u), __uint_as_float(w.w << 16), __uint_as_float(w.w & 0xffff0000u)}; }
;                     v0 = v0 + acc[ai][bj][m][0]; v1 = v1 + acc[ai][bj][m][1];
;                     if (fout) { *(f32x4*)(fout + (size_t)row * DM + col) = v0; *(f32x4*)(fout + (size_t)row * DM + col + 4) = v1; }
;                     else { u32x4 w; w.x = cvtpk(v0[0], v0[1]); w.y = cvtpk(v0[2], v0[3]); w.z = cvtpk(v1[0], v1[1]); w.w = cvtpk(v1[2], v1[3]); *(u32x4*)(XR + (size_t)row * DM + col) = w; }
.LBB0_922:
	v_add_u32_e32 v64, 0x80, v140
	v_ashrrev_i32_e32 v65, 31, v64
	v_lshlrev_b64 v[66:67], 11, v[64:65]
	v_lshl_add_u64 v[66:67], s[12:13], 0, v[66:67]
	v_lshl_add_u64 v[66:67], v[138:139], 1, v[66:67]
	global_load_dwordx4 v[68:71], v[66:67], off
	v_lshlrev_b64 v[72:73], 10, v[64:65]
	s_and_b64 vcc, exec, s[6:7]
	s_waitcnt vmcnt(0)
	v_lshlrev_b32_e32 v74, 16, v68
	v_and_b32_e32 v75, 0xffff0000, v68
	v_lshlrev_b32_e32 v68, 16, v69
	v_and_b32_e32 v69, 0xffff0000, v69
	v_lshlrev_b32_e32 v76, 16, v70
	v_and_b32_e32 v77, 0xffff0000, v70
	v_lshlrev_b32_e32 v70, 16, v71
	v_and_b32_e32 v71, 0xffff0000, v71
	v_pk_add_f32 v[62:63], v[62:63], v[68:69]
	v_pk_add_f32 v[60:61], v[60:61], v[74:75]
	v_pk_add_f32 v[58:59], v[58:59], v[70:71]
	v_pk_add_f32 v[56:57], v[56:57], v[76:77]
	v_lshl_add_u64 v[68:69], v[72:73], 2, s[16:17]
	s_cbranch_vccnz .LBB0_973
	v_lshl_add_u64 v[70:71], v[138:139], 2, v[68:69]
	global_store_dwordx4 v[70:71], v[60:63], off nt
	global_store_dwordx4 v[70:71], v[56:59], off offset:16 nt
	s_cbranch_execnz .LBB0_925

; __device__ __forceinline__ unsigned cvtpk(float lo, float hi) { f32x2 v = {lo, hi}; bf16x2_t b = __builtin_convertvector(v, bf16x2_t); return __builtin_bit_cast(unsigned, b); }
;     __device__ __forceinline__ void operator()(const f32x4 (&acc)[2][2][4][2], const Unit& u, int wr, int wc, int fr, int fq) const {
;     ...
;                 for (int bj = 0; bj < 2; ++bj) { const int col = u.pn * BM + bj * HALF + wc * 32 + 8 * fq;
;                     f32x4 v0, v1;
;                     if (xin_p) { const float* xr = (row < MP ? xin_p + (size_t)row * DM : xin_s + (size_t)(row - MP) * DM) + col; v0 = *(const f32x4*)xr; v1 = *(const f32x4*)(xr + 4); }
;                     else { const u32x4 w = *(const u32x4*)(XR + (size_t)row * DM + col);
;                         v0 = (f32x4){__uint_as_float(w.x << 16), __uint_as_float(w.x & 0xffff0000u), __uint_as_float(w.y << 16), __uint_as_float(w.y & 0xffff0000u)};
;                         v1 = (f32x4){__uint_as_float(w.z << 16), __uint_as_float(w.z & 0xffff0000u), __uint_as_float(w.w << 16), __uint_as_float(w.w & 0xffff0000u)}; }
;                     v0 = v0 + acc[ai][bj][m][0]; v1 = v1 + acc[ai][bj][m][1];
;                     if (fout) { *(f32x4*)(fout + (size_t)row * DM + col) = v0; *(f32x4*)(fout + (size_t)row * DM + col + 4) = v1; }
;                     else { u32x4 w; w.x = cvtpk(v0[0], v0[1]); w.y = cvtpk(v0[2], v0[3]); w.z = cvtpk(v1[0], v1[1]); w.w = cvtpk(v1[2], v1[3]); *(u32x4*)(XR + (size_t)row * DM + col) = w; }
.LBB0_925:
	global_load_dwordx4 v[70:73], v[66:67], off offset:256
	s_and_b64 vcc, exec, s[6:7]
	s_waitcnt vmcnt(0)
	v_lshlrev_b32_e32 v74, 16, v70
	v_and_b32_e32 v75, 0xffff0000, v70
	v_lshlrev_b32_e32 v70, 16, v71
	v_and_b32_e32 v71, 0xffff0000, v71
	v_lshlrev_b32_e32 v76, 16, v72
	v_and_b32_e32 v77, 0xffff0000, v72
	v_lshlrev_b32_e32 v72, 16, v73
	v_and_b32_e32 v73, 0xffff0000, v73
	v_pk_add_f32 v[54:55], v[54:55], v[70:71]
	v_pk_add_f32 v[52:53], v[52:53], v[74:75]
	v_pk_add_f32 v[50:51], v[50:51], v[72:73]
	v_pk_add_f32 v[48:49], v[48:49], v[76:77]
	s_cbranch_vccnz .LBB0_974
	v_lshl_add_u64 v[68:69], v[138:139], 2, v[68:69]
	global_store_dwordx4 v[68:69], v[52:55], off offset:512 nt
	global_store_dwordx4 v[68:69], v[48:51], off offset:528 nt
	s_cbranch_execnz .LBB0_928

; __device__ __forceinline__ unsigned cvtpk(float lo, float hi) { f32x2 v = {lo, hi}; bf16x2_t b = __builtin_convertvector(v, bf16x2_t); return __builtin_bit_cast(unsigned, b); }
;     __device__ __forceinline__ void operator()(const f32x4 (&acc)[2][2][4][2], const Unit& u, int wr, int wc, int fr, int fq) const {
;     ...
;                 for (int bj = 0; bj < 2; ++bj) { const int col = u.pn * BM + bj * HALF + wc * 32 + 8 * fq;
;                     f32x4 v0, v1;
;                     if (xin_p) { const float* xr = (row < MP ? xin_p + (size_t)row * DM : xin_s + (size_t)(row - MP) * DM) + col; v0 = *(const f32x4*)xr; v1 = *(const f32x4*)(xr + 4); }
;                     else { const u32x4 w = *(const u32x4*)(XR + (size_t)row * DM + col);
;                         v0 = (f32x4){__uint_as_float(w.x << 16), __uint_as_float(w.x & 0xffff0000u), __uint_as_float(w.y << 16), __uint_as_float(w.y & 0xffff0000u)};
;                         v1 = (f32x4){__uint_as_float(w.z << 16), __uint_as_float(w.z & 0xffff0000u), __uint_as_float(w.w << 16), __uint_as_float(w.w & 0xffff0000u)}; }
;                     v0 = v0 + acc[ai][bj][m][0]; v1 = v1 + acc[ai][bj][m][1];
;                     if (fout) { *(f32x4*)(fout + (size_t)row * DM + col) = v0; *(f32x4*)(fout + (size_t)row * DM + col + 4) = v1; }
;                     else { u32x4 w; w.x = cvtpk(v0[0], v0[1]); w.y = cvtpk(v0[2], v0[3]); w.z = cvtpk(v1[0], v1[1]); w.w = cvtpk(v1[2], v1[3]); *(u32x4*)(XR + (size_t)row * DM + col) = w; }
.LBB0_932:
	v_add_u32_e32 v48, 0x90, v140
	v_ashrrev_i32_e32 v49, 31, v48
	v_lshlrev_b64 v[50:51], 11, v[48:49]
	v_lshl_add_u64 v[50:51], s[12:13], 0, v[50:51]
	v_lshl_add_u64 v[50:51], v[138:139], 1, v[50:51]
	global_load_dwordx4 v[52:55], v[50:51], off
	v_lshlrev_b64 v[56:57], 10, v[48:49]
	s_and_b64 vcc, exec, s[6:7]
	s_waitcnt vmcnt(0)
	v_lshlrev_b32_e32 v58, 16, v52
	v_and_b32_e32 v59, 0xffff0000, v52
	v_lshlrev_b32_e32 v52, 16, v53
	v_and_b32_e32 v53, 0xffff0000, v53
	v_lshlrev_b32_e32 v60, 16, v54
	v_and_b32_e32 v61, 0xffff0000, v54
	v_lshlrev_b32_e32 v54, 16, v55
	v_and_b32_e32 v55, 0xffff0000, v55
	v_pk_add_f32 v[46:47], v[46:47], v[52:53]
	v_pk_add_f32 v[44:45], v[44:45], v[58:59]
	v_pk_add_f32 v[42:43], v[42:43], v[54:55]
	v_pk_add_f32 v[40:41], v[40:41], v[60:61]
	v_lshl_add_u64 v[52:53], v[56:57], 2, s[16:17]
	s_cbranch_vccnz .LBB0_975
	v_lshl_add_u64 v[54:55], v[138:139], 2, v[52:53]
	global_store_dwordx4 v[54:55], v[44:47], off nt
	global_store_dwordx4 v[54:55], v[40:43], off offset:16 nt
	s_cbranch_execnz .LBB0_935

; __device__ __forceinline__ unsigned cvtpk(float lo, float hi) { f32x2 v = {lo, hi}; bf16x2_t b = __builtin_convertvector(v, bf16x2_t); return __builtin_bit_cast(unsigned, b); }
;     __device__ __forceinline__ void operator()(const f32x4 (&acc)[2][2][4][2], const Unit& u, int wr, int wc, int fr, int fq) const {
;     ...
;                 for (int bj = 0; bj < 2; ++bj) { const int col = u.pn * BM + bj * HALF + wc * 32 + 8 * fq;
;                     f32x4 v0, v1;
;                     if (xin_p) { const float* xr = (row < MP ? xin_p + (size_t)row * DM : xin_s + (size_t)(row - MP) * DM) + col; v0 = *(const f32x4*)xr; v1 = *(const f32x4*)(xr + 4); }
;                     else { const u32x4 w = *(const u32x4*)(XR + (size_t)row * DM + col);
;                         v0 = (f32x4){__uint_as_float(w.x << 16), __uint_as_float(w.x & 0xffff0000u), __uint_as_float(w.y << 16), __uint_as_float(w.y & 0xffff0000u)};
;                         v1 = (f32x4){__uint_as_float(w.z << 16), __uint_as_float(w.z & 0xffff0000u), __uint_as_float(w.w << 16), __uint_as_float(w.w & 0xffff0000u)}; }
;                     v0 = v0 + acc[ai][bj][m][0]; v1 = v1 + acc[ai][bj][m][1];
;                     if (fout) { *(f32x4*)(fout + (size_t)row * DM + col) = v0; *(f32x4*)(fout + (size_t)row * DM + col + 4) = v1; }
;                     else { u32x4 w; w.x = cvtpk(v0[0], v0[1]); w.y = cvtpk(v0[2], v0[3]); w.z = cvtpk(v1[0], v1[1]); w.w = cvtpk(v1[2], v1[3]); *(u32x4*)(XR + (size_t)row * DM + col) = w; }
.LBB0_935:
	global_load_dwordx4 v[54:57], v[50:51], off offset:256
	s_and_b64 vcc, exec, s[6:7]
	s_waitcnt vmcnt(0)
	v_lshlrev_b32_e32 v58, 16, v54
	v_and_b32_e32 v59, 0xffff0000, v54
	v_lshlrev_b32_e32 v54, 16, v55
	v_and_b32_e32 v55, 0xffff0000, v55
	v_lshlrev_b32_e32 v60, 16, v56
	v_and_b32_e32 v61, 0xffff0000, v56
	v_lshlrev_b32_e32 v56, 16, v57
	v_and_b32_e32 v57, 0xffff0000, v57
	v_pk_add_f32 v[38:39], v[38:39], v[54:55]
	v_pk_add_f32 v[36:37], v[36:37], v[58:59]
	v_pk_add_f32 v[34:35], v[34:35], v[56:57]
	v_pk_add_f32 v[32:33], v[32:33], v[60:61]
	s_cbranch_vccnz .LBB0_976
	v_lshl_add_u64 v[52:53], v[138:139], 2, v[52:53]
	global_store_dwordx4 v[52:53], v[36:39], off offset:512 nt
	global_store_dwordx4 v[52:53], v[32:35], off offset:528 nt
	s_cbranch_execnz .LBB0_938

; __device__ __forceinline__ unsigned cvtpk(float lo, float hi) { f32x2 v = {lo, hi}; bf16x2_t b = __builtin_convertvector(v, bf16x2_t); return __builtin_bit_cast(unsigned, b); }
;     __device__ __forceinline__ void operator()(const f32x4 (&acc)[2][2][4][2], const Unit& u, int wr, int wc, int fr, int fq) const {
;     ...
;                 for (int bj = 0; bj < 2; ++bj) { const int col = u.pn * BM + bj * HALF + wc * 32 + 8 * fq;
;                     f32x4 v0, v1;
;                     if (xin_p) { const float* xr = (row < MP ? xin_p + (size_t)row * DM : xin_s + (size_t)(row - MP) * DM) + col; v0 = *(const f32x4*)xr; v1 = *(const f32x4*)(xr + 4); }
;                     else { const u32x4 w = *(const u32x4*)(XR + (size_t)row * DM + col);
;                         v0 = (f32x4){__uint_as_float(w.x << 16), __uint_as_float(w.x & 0xffff0000u), __uint_as_float(w.y << 16), __uint_as_float(w.y & 0xffff0000u)};
;                         v1 = (f32x4){__uint_as_float(w.z << 16), __uint_as_float(w.z & 0xffff0000u), __uint_as_float(w.w << 16), __uint_as_float(w.w & 0xffff0000u)}; }
;                     v0 = v0 + acc[ai][bj][m][0]; v1 = v1 + acc[ai][bj][m][1];
;                     if (fout) { *(f32x4*)(fout + (size_t)row * DM + col) = v0; *(f32x4*)(fout + (size_t)row * DM + col + 4) = v1; }
;                     else { u32x4 w; w.x = cvtpk(v0[0], v0[1]); w.y = cvtpk(v0[2], v0[3]); w.z = cvtpk(v1[0], v1[1]); w.w = cvtpk(v1[2], v1[3]); *(u32x4*)(XR + (size_t)row * DM + col) = w; }
.LBB0_942:
	v_add_u32_e32 v32, 0xa0, v140
	v_ashrrev_i32_e32 v33, 31, v32
	v_lshlrev_b64 v[34:35], 11, v[32:33]
	v_lshl_add_u64 v[34:35], s[12:13], 0, v[34:35]
	v_lshl_add_u64 v[34:35], v[138:139], 1, v[34:35]
	global_load_dwordx4 v[36:39], v[34:35], off
	v_lshlrev_b64 v[40:41], 10, v[32:33]
	s_and_b64 vcc, exec, s[6:7]
	s_waitcnt vmcnt(0)
	v_lshlrev_b32_e32 v42, 16, v36
	v_and_b32_e32 v43, 0xffff0000, v36
	v_lshlrev_b32_e32 v36, 16, v37
	v_and_b32_e32 v37, 0xffff0000, v37
	v_lshlrev_b32_e32 v44, 16, v38
	v_and_b32_e32 v45, 0xffff0000, v38
	v_lshlrev_b32_e32 v38, 16, v39
	v_and_b32_e32 v39, 0xffff0000, v39
	v_pk_add_f32 v[30:31], v[30:31], v[36:37]
	v_pk_add_f32 v[28:29], v[28:29], v[42:43]
	v_pk_add_f32 v[26:27], v[26:27], v[38:39]
	v_pk_add_f32 v[24:25], v[24:25], v[44:45]
	v_lshl_add_u64 v[36:37], v[40:41], 2, s[16:17]
	s_cbranch_vccnz .LBB0_977
	v_lshl_add_u64 v[38:39], v[138:139], 2, v[36:37]
	global_store_dwordx4 v[38:39], v[28:31], off nt
	global_store_dwordx4 v[38:39], v[24:27], off offset:16 nt
	s_cbranch_execnz .LBB0_945

; __device__ __forceinline__ unsigned cvtpk(float lo, float hi) { f32x2 v = {lo, hi}; bf16x2_t b = __builtin_convertvector(v, bf16x2_t); return __builtin_bit_cast(unsigned, b); }
;     __device__ __forceinline__ void operator()(const f32x4 (&acc)[2][2][4][2], const Unit& u, int wr, int wc, int fr, int fq) const {
;     ...
;                 for (int bj = 0; bj < 2; ++bj) { const int col = u.pn * BM + bj * HALF + wc * 32 + 8 * fq;
;                     f32x4 v0, v1;
;                     if (xin_p) { const float* xr = (row < MP ? xin_p + (size_t)row * DM : xin_s + (size_t)(row - MP) * DM) + col; v0 = *(const f32x4*)xr; v1 = *(const f32x4*)(xr + 4); }
;                     else { const u32x4 w = *(const u32x4*)(XR + (size_t)row * DM + col);
;                         v0 = (f32x4){__uint_as_float(w.x << 16), __uint_as_float(w.x & 0xffff0000u), __uint_as_float(w.y << 16), __uint_as_float(w.y & 0xffff0000u)};
;                         v1 = (f32x4){__uint_as_float(w.z << 16), __uint_as_float(w.z & 0xffff0000u), __uint_as_float(w.w << 16), __uint_as_float(w.w & 0xffff0000u)}; }
;                     v0 = v0 + acc[ai][bj][m][0]; v1 = v1 + acc[ai][bj][m][1];
;                     if (fout) { *(f32x4*)(fout + (size_t)row * DM + col) = v0; *(f32x4*)(fout + (size_t)row * DM + col + 4) = v1; }
;                     else { u32x4 w; w.x = cvtpk(v0[0], v0[1]); w.y = cvtpk(v0[2], v0[3]); w.z = cvtpk(v1[0], v1[1]); w.w = cvtpk(v1[2], v1[3]); *(u32x4*)(XR + (size_t)row * DM + col) = w; }
.LBB0_945:
	global_load_dwordx4 v[38:41], v[34:35], off offset:256
	s_and_b64 vcc, exec, s[6:7]
	s_waitcnt vmcnt(0)
	v_lshlrev_b32_e32 v42, 16, v38
	v_and_b32_e32 v43, 0xffff0000, v38
	v_lshlrev_b32_e32 v38, 16, v39
	v_and_b32_e32 v39, 0xffff0000, v39
	v_lshlrev_b32_e32 v44, 16, v40
	v_and_b32_e32 v45, 0xffff0000, v40
	v_lshlrev_b32_e32 v40, 16, v41
	v_and_b32_e32 v41, 0xffff0000, v41
	v_pk_add_f32 v[22:23], v[22:23], v[38:39]
	v_pk_add_f32 v[20:21], v[20:21], v[42:43]
	v_pk_add_f32 v[18:19], v[18:19], v[40:41]
	v_pk_add_f32 v[16:17], v[16:17], v[44:45]
	s_cbranch_vccnz .LBB0_978
	v_lshl_add_u64 v[36:37], v[138:139], 2, v[36:37]
	global_store_dwordx4 v[36:37], v[20:23], off offset:512 nt
	global_store_dwordx4 v[36:37], v[16:19], off offset:528 nt
	s_cbranch_execnz .LBB0_948

; __device__ __forceinline__ unsigned cvtpk(float lo, float hi) { f32x2 v = {lo, hi}; bf16x2_t b = __builtin_convertvector(v, bf16x2_t); return __builtin_bit_cast(unsigned, b); }
;     __device__ __forceinline__ void operator()(const f32x4 (&acc)[2][2][4][2], const Unit& u, int wr, int wc, int fr, int fq) const {
;     ...
;                 for (int bj = 0; bj < 2; ++bj) { const int col = u.pn * BM + bj * HALF + wc * 32 + 8 * fq;
;                     f32x4 v0, v1;
;                     if (xin_p) { const float* xr = (row < MP ? xin_p + (size_t)row * DM : xin_s + (size_t)(row - MP) * DM) + col; v0 = *(const f32x4*)xr; v1 = *(const f32x4*)(xr + 4); }
;                     else { const u32x4 w = *(const u32x4*)(XR + (size_t)row * DM + col);
;                         v0 = (f32x4){__uint_as_float(w.x << 16), __uint_as_float(w.x & 0xffff0000u), __uint_as_float(w.y << 16), __uint_as_float(w.y & 0xffff0000u)};
;                         v1 = (f32x4){__uint_as_float(w.z << 16), __uint_as_float(w.z & 0xffff0000u), __uint_as_float(w.w << 16), __uint_as_float(w.w & 0xffff0000u)}; }
;                     v0 = v0 + acc[ai][bj][m][0]; v1 = v1 + acc[ai][bj][m][1];
;                     if (fout) { *(f32x4*)(fout + (size_t)row * DM + col) = v0; *(f32x4*)(fout + (size_t)row * DM + col + 4) = v1; }
;                     else { u32x4 w; w.x = cvtpk(v0[0], v0[1]); w.y = cvtpk(v0[2], v0[3]); w.z = cvtpk(v1[0], v1[1]); w.w = cvtpk(v1[2], v1[3]); *(u32x4*)(XR + (size_t)row * DM + col) = w; }
.LBB0_952:
	v_add_u32_e32 v16, 0xb0, v140
	v_ashrrev_i32_e32 v17, 31, v16
	v_lshlrev_b64 v[18:19], 11, v[16:17]
	v_lshl_add_u64 v[18:19], s[12:13], 0, v[18:19]
	v_lshl_add_u64 v[18:19], v[138:139], 1, v[18:19]
	global_load_dwordx4 v[20:23], v[18:19], off
	v_lshlrev_b64 v[24:25], 10, v[16:17]
	s_and_b64 vcc, exec, s[6:7]
	s_waitcnt vmcnt(0)
	v_lshlrev_b32_e32 v26, 16, v20
	v_and_b32_e32 v27, 0xffff0000, v20
	v_lshlrev_b32_e32 v20, 16, v21
	v_and_b32_e32 v21, 0xffff0000, v21
	v_lshlrev_b32_e32 v28, 16, v22
	v_and_b32_e32 v29, 0xffff0000, v22
	v_lshlrev_b32_e32 v22, 16, v23
	v_and_b32_e32 v23, 0xffff0000, v23
	v_pk_add_f32 v[14:15], v[14:15], v[20:21]
	v_pk_add_f32 v[12:13], v[12:13], v[26:27]
	v_pk_add_f32 v[10:11], v[10:11], v[22:23]
	v_pk_add_f32 v[8:9], v[8:9], v[28:29]
	v_lshl_add_u64 v[20:21], v[24:25], 2, s[16:17]
	s_cbranch_vccnz .LBB0_979
	v_lshl_add_u64 v[22:23], v[138:139], 2, v[20:21]
	global_store_dwordx4 v[22:23], v[12:15], off nt
	global_store_dwordx4 v[22:23], v[8:11], off offset:16 nt
	s_cbranch_execnz .LBB0_955

; __device__ __forceinline__ unsigned cvtpk(float lo, float hi) { f32x2 v = {lo, hi}; bf16x2_t b = __builtin_convertvector(v, bf16x2_t); return __builtin_bit_cast(unsigned, b); }
;     __device__ __forceinline__ void operator()(const f32x4 (&acc)[2][2][4][2], const Unit& u, int wr, int wc, int fr, int fq) const {
;     ...
;                 for (int bj = 0; bj < 2; ++bj) { const int col = u.pn * BM + bj * HALF + wc * 32 + 8 * fq;
;                     f32x4 v0, v1;
;                     if (xin_p) { const float* xr = (row < MP ? xin_p + (size_t)row * DM : xin_s + (size_t)(row - MP) * DM) + col; v0 = *(const f32x4*)xr; v1 = *(const f32x4*)(xr + 4); }
;                     else { const u32x4 w = *(const u32x4*)(XR + (size_t)row * DM + col);
;                         v0 = (f32x4){__uint_as_float(w.x << 16), __uint_as_float(w.x & 0xffff0000u), __uint_as_float(w.y << 16), __uint_as_float(w.y & 0xffff0000u)};
;                         v1 = (f32x4){__uint_as_float(w.z << 16), __uint_as_float(w.z & 0xffff0000u), __uint_as_float(w.w << 16), __uint_as_float(w.w & 0xffff0000u)}; }
;                     v0 = v0 + acc[ai][bj][m][0]; v1 = v1 + acc[ai][bj][m][1];
;                     if (fout) { *(f32x4*)(fout + (size_t)row * DM + col) = v0; *(f32x4*)(fout + (size_t)row * DM + col + 4) = v1; }
;                     else { u32x4 w; w.x = cvtpk(v0[0], v0[1]); w.y = cvtpk(v0[2], v0[3]); w.z = cvtpk(v1[0], v1[1]); w.w = cvtpk(v1[2], v1[3]); *(u32x4*)(XR + (size_t)row * DM + col) = w; }
.LBB0_955:
	global_load_dwordx4 v[22:25], v[18:19], off offset:256
	s_and_b64 vcc, exec, s[6:7]
	s_waitcnt vmcnt(0)
	v_lshlrev_b32_e32 v26, 16, v22
	v_and_b32_e32 v27, 0xffff0000, v22
	v_lshlrev_b32_e32 v22, 16, v23
	v_and_b32_e32 v23, 0xffff0000, v23
	v_lshlrev_b32_e32 v28, 16, v24
	v_and_b32_e32 v29, 0xffff0000, v24
	v_lshlrev_b32_e32 v24, 16, v25
	v_and_b32_e32 v25, 0xffff0000, v25
	v_pk_add_f32 v[6:7], v[6:7], v[22:23]
	v_pk_add_f32 v[4:5], v[4:5], v[26:27]
	v_pk_add_f32 v[2:3], v[2:3], v[24:25]
	v_pk_add_f32 v[0:1], v[0:1], v[28:29]
	s_cbranch_vccnz .LBB0_980
	v_lshl_add_u64 v[20:21], v[138:139], 2, v[20:21]
	global_store_dwordx4 v[20:21], v[4:7], off offset:512 nt
	global_store_dwordx4 v[20:21], v[0:3], off offset:528 nt
	s_cbranch_execnz .LBB0_958
